# PEER top-k key encoding: float->sortable key in 2 instructions (ashr + bitop3 with sign constant in vcc_lo) instead of 4, 64 elements
# speedup vs baseline: 1.0173x; 1.0054x over previous
; DEV f32x16 mfma32(bf16x8 a, bf16x8 b, f32x16 c) { return __builtin_amdgcn_mfma_f32_32x32x16_bf16(a, b, c, 0, 0, 0); }
; DEV void gemm_core(const bf16_t* __restrict__ A, const bf16_t* __restrict__ Bt, int m0, int n0, bf16_t* As, bf16_t* Bs, int tid,
;                    f32x16 (&acc)[2][2]) {
;     ...
;   for (int kt = 0; kt < 16; ++kt) {
;     __syncthreads();
;     {
;       bf16_t* as = As + lrow * 72 + lc8; bf16_t* bs = Bs + lrow * 72 + lc8;
;       *(uint4*)(as) = ra0; *(uint4*)(as + 32 * 72) = ra1; *(uint4*)(as + 64 * 72) = ra2; *(uint4*)(as + 96 * 72) = ra3;
;       *(uint4*)(bs) = rb0; *(uint4*)(bs + 32 * 72) = rb1; *(uint4*)(bs + 64 * 72) = rb2; *(uint4*)(bs + 96 * 72) = rb3;
;     }
;     __syncthreads();
;     {
;       const int k0 = (kt + 1 < 16) ? (kt + 1) * 64 : 15 * 64;
;       GLOAD(k0);
;     }
; #pragma unroll
;     for (int kk = 0; kk < 4; ++kk) {
;       bf16x8 af[2], bfr[2];
; #pragma unroll
;       for (int mi = 0; mi < 2; ++mi) af[mi] = *(const bf16x8*)(As + (wm * 64 + mi * 32 + lr) * 72 + kk * 16 + hk * 8);
; #pragma unroll
;       for (int ni = 0; ni < 2; ++ni) bfr[ni] = *(const bf16x8*)(Bs + (wn * 64 + ni * 32 + lr) * 72 + kk * 16 + hk * 8);
; #pragma unroll
;       for (int mi = 0; mi < 2; ++mi)
; #pragma unroll
;         for (int ni = 0; ni < 2; ++ni) acc[mi][ni] = mfma32(af[mi], bfr[ni], acc[mi][ni]);
;     }
;   }
.LBB0_46:
	s_barrier
	s_waitcnt vmcnt(6)
	ds_write_b128 v98, v[68:71]
	s_waitcnt vmcnt(5)
	ds_write_b128 v98, v[72:75] offset:4608
	s_waitcnt vmcnt(4)
	ds_write_b128 v98, v[76:79] offset:9216
	s_waitcnt vmcnt(3)
	ds_write_b128 v98, v[80:83] offset:13824
	s_waitcnt vmcnt(3)
	ds_write_b128 v98, v[64:67] offset:18432
	s_waitcnt vmcnt(2)
	ds_write_b128 v98, v[84:87] offset:23040
	s_waitcnt vmcnt(1)
	ds_write_b128 v98, v[88:91] offset:27648
	s_waitcnt vmcnt(0)
	ds_write_b128 v98, v[92:95] offset:32256
	s_waitcnt lgkmcnt(0)
	s_barrier
	ds_read_b128 v[64:67], v189
	ds_read_b128 v[68:71], v190 offset:18432
	ds_read_b128 v[72:75], v189 offset:32
	ds_read_b128 v[76:79], v190 offset:18464
	ds_read_b128 v[80:83], v190 offset:23040
	ds_read_b128 v[84:87], v190 offset:23072
	s_waitcnt lgkmcnt(4)
	v_mfma_f32_32x32x16_bf16 v[48:63], v[64:67], v[68:71], v[48:63]
	s_waitcnt lgkmcnt(1)
	v_mfma_f32_32x32x16_bf16 v[32:47], v[64:67], v[80:83], v[32:47]
	ds_read_b128 v[64:67], v189 offset:4608
	ds_read_b128 v[88:91], v189 offset:4640
	s_waitcnt lgkmcnt(1)
	v_mfma_f32_32x32x16_bf16 v[16:31], v[64:67], v[68:71], v[16:31]
	v_mfma_f32_32x32x16_bf16 v[48:63], v[72:75], v[76:79], v[48:63]
	v_mfma_f32_32x32x16_bf16 v[32:47], v[72:75], v[84:87], v[32:47]
	v_mfma_f32_32x32x16_bf16 v[0:15], v[64:67], v[80:83], v[0:15]
	ds_read_b128 v[64:67], v189 offset:64
	ds_read_b128 v[68:71], v190 offset:18496
	ds_read_b128 v[72:75], v189 offset:96
	ds_read_b128 v[92:95], v190 offset:18528
	v_lshl_add_u64 v[80:81], v[148:149], 0, s[38:39]
	v_lshl_add_u64 v[82:83], v[150:151], 0, s[38:39]
	s_add_u32 s38, s38, 0x80
	s_addc_u32 s39, s39, 0
	s_cmpk_lg_i32 s38, 0x780
	s_waitcnt lgkmcnt(4)
	v_mfma_f32_32x32x16_bf16 v[16:31], v[88:91], v[76:79], v[16:31]
	ds_read_b128 v[76:79], v190 offset:23104
	ds_read_b128 v[192:195], v190 offset:23136
	ds_read_b128 v[196:199], v189 offset:4704
	s_waitcnt lgkmcnt(5)
	v_mfma_f32_32x32x16_bf16 v[48:63], v[64:67], v[68:71], v[48:63]
	s_waitcnt lgkmcnt(2)
	v_mfma_f32_32x32x16_bf16 v[32:47], v[64:67], v[76:79], v[32:47]
	ds_read_b128 v[64:67], v189 offset:4672
	v_mfma_f32_32x32x16_bf16 v[0:15], v[88:91], v[84:87], v[0:15]
	v_add_co_u32_e32 v84, vcc, s42, v80
	s_nop 1
	v_addc_co_u32_e32 v85, vcc, 0, v81, vcc
	v_add_co_u32_e32 v86, vcc, s43, v80
	s_waitcnt lgkmcnt(0)
	v_mfma_f32_32x32x16_bf16 v[16:31], v[64:67], v[68:71], v[16:31]
	v_addc_co_u32_e32 v87, vcc, 0, v81, vcc
	v_add_co_u32_e32 v88, vcc, s44, v80
	s_nop 1
	v_addc_co_u32_e32 v89, vcc, 0, v81, vcc
	v_add_co_u32_e32 v90, vcc, s42, v82
	v_mfma_f32_32x32x16_bf16 v[0:15], v[64:67], v[76:79], v[0:15]
	s_nop 0
	v_addc_co_u32_e32 v91, vcc, 0, v83, vcc
	v_add_co_u32_e32 v200, vcc, s43, v82
	global_load_dwordx4 v[64:67], v[82:83], off offset:128
	s_nop 0
	v_addc_co_u32_e32 v201, vcc, 0, v83, vcc
	v_add_co_u32_e32 v228, vcc, s44, v82
	v_mfma_f32_32x32x16_bf16 v[48:63], v[72:75], v[92:95], v[48:63]
	s_nop 0
	v_addc_co_u32_e32 v229, vcc, 0, v83, vcc
	v_mfma_f32_32x32x16_bf16 v[32:47], v[72:75], v[192:195], v[32:47]
	global_load_dwordx4 v[68:71], v[80:81], off offset:128
	global_load_dwordx4 v[72:75], v[84:85], off offset:128
	global_load_dwordx4 v[76:79], v[86:87], off offset:128
	s_nop 0
	global_load_dwordx4 v[80:83], v[88:89], off offset:128
	global_load_dwordx4 v[84:87], v[90:91], off offset:128
	s_nop 0
	global_load_dwordx4 v[88:91], v[200:201], off offset:128
	v_mfma_f32_32x32x16_bf16 v[16:31], v[196:199], v[92:95], v[16:31]
	global_load_dwordx4 v[92:95], v[228:229], off offset:128
	v_mfma_f32_32x32x16_bf16 v[0:15], v[196:199], v[192:195], v[0:15]
	s_cbranch_scc1 .LBB0_46
	s_barrier
	s_waitcnt vmcnt(6)
	ds_write_b128 v98, v[68:71]
	s_waitcnt vmcnt(5)
	ds_write_b128 v98, v[72:75] offset:4608
	s_waitcnt vmcnt(4)
	ds_write_b128 v98, v[76:79] offset:9216
	s_waitcnt vmcnt(3)
	ds_write_b128 v98, v[80:83] offset:13824
	ds_write_b128 v98, v[64:67] offset:18432
	s_waitcnt vmcnt(2)
	ds_write_b128 v98, v[84:87] offset:23040
	s_waitcnt vmcnt(1)
	ds_write_b128 v98, v[88:91] offset:27648
	s_waitcnt vmcnt(0)
	ds_write_b128 v98, v[92:95] offset:32256
	s_waitcnt lgkmcnt(0)
	s_barrier
	ds_read_b128 v[64:67], v189 offset:4608
	ds_read_b128 v[68:71], v190 offset:23040
	ds_read_b128 v[72:75], v189
	ds_read_b128 v[76:79], v189 offset:32
	ds_read_b128 v[80:83], v190 offset:18432
	ds_read_b128 v[84:87], v190 offset:18464
	s_waitcnt lgkmcnt(1)
	v_mfma_f32_32x32x16_bf16 v[48:63], v[72:75], v[80:83], v[48:63]
	v_readlane_b32 s38, v249, 58
	s_or_b32 s38, s41, s38
	s_ashr_i32 s39, s38, 31
	s_lshl_b64 s[38:39], s[38:39], 8
	s_movk_i32 s41, 0x80
	v_mfma_f32_32x32x16_bf16 v[32:47], v[72:75], v[68:71], v[32:47]
	v_mfma_f32_32x32x16_bf16 v[16:31], v[64:67], v[80:83], v[16:31]
	v_mfma_f32_32x32x16_bf16 v[0:15], v[64:67], v[68:71], v[0:15]
	ds_read_b128 v[64:67], v189 offset:4640
	ds_read_b128 v[68:71], v190 offset:23072
	s_waitcnt lgkmcnt(2)
	v_mfma_f32_32x32x16_bf16 v[48:63], v[76:79], v[84:87], v[48:63]
	s_waitcnt lgkmcnt(0)
	v_mfma_f32_32x32x16_bf16 v[32:47], v[76:79], v[68:71], v[32:47]
	v_mfma_f32_32x32x16_bf16 v[16:31], v[64:67], v[84:87], v[16:31]
	v_mfma_f32_32x32x16_bf16 v[0:15], v[64:67], v[68:71], v[0:15]
	ds_read_b128 v[64:67], v189 offset:64
	ds_read_b128 v[68:71], v189 offset:4672
	ds_read_b128 v[72:75], v190 offset:18496
	ds_read_b128 v[76:79], v190 offset:23104
	s_waitcnt lgkmcnt(1)
	v_mfma_f32_32x32x16_bf16 v[48:63], v[64:67], v[72:75], v[48:63]
	s_waitcnt lgkmcnt(0)
	v_mfma_f32_32x32x16_bf16 v[32:47], v[64:67], v[76:79], v[32:47]
	v_mfma_f32_32x32x16_bf16 v[16:31], v[68:71], v[72:75], v[16:31]
	v_mfma_f32_32x32x16_bf16 v[0:15], v[68:71], v[76:79], v[0:15]
	ds_read_b128 v[64:67], v189 offset:96
	ds_read_b128 v[68:71], v189 offset:4704
	ds_read_b128 v[72:75], v190 offset:18528
	ds_read_b128 v[76:79], v190 offset:23136
	s_waitcnt lgkmcnt(1)
; DEV unsigned short f2bf(float f) { return (unsigned short)(pack2(f, 0.f) & 0xFFFFu); }
; __device__ void peer_q_topk_item(const Params& P, int l, int item, char* smem) {
;     ...
; #pragma unroll
;       for (int mi = 0; mi < 2; ++mi)
; #pragma unroll
;         for (int ni = 0; ni < 2; ++ni) {
;           const int col = wn * 64 + ni * 32 + lr;
;           const int rbase = wm * 64 + mi * 32 + 4 * hk;
; #pragma unroll
;           for (int i = 0; i < 16; ++i) Qs[(rbase + (i & 3) + 8 * (i >> 2)) * 136 + col] = f2bf(acc[mi][ni][i]);
;         }
;     }
;     __syncthreads();
;     {
;       const bf16_t* skg = P.SK + (size_t)((l * 2 + c) * 128) * 128;
; #pragma unroll
;       for (int k = 0; k < 8; ++k) {
;         const int ch = tid + 256 * k;
;         const int row = ch >> 4, c8 = (ch & 15) * 8;
;         *(uint4*)(As + row * 136 + c8) = *(const uint4*)(skg + row * 128 + c8);
;       }
	v_mfma_f32_32x32x16_bf16 v[48:63], v[64:67], v[72:75], v[48:63]
	s_waitcnt lgkmcnt(0)
	v_mfma_f32_32x32x16_bf16 v[32:47], v[64:67], v[76:79], v[32:47]
	s_nop 9
	v_cvt_pk_bf16_f32 v48, v48, s0
	ds_write_b16 v102, v48 offset:36864
	v_cvt_pk_bf16_f32 v48, v49, s0
	ds_write_b16 v183, v48 offset:36864
	v_cvt_pk_bf16_f32 v48, v50, s0
	ds_write_b16 v184, v48 offset:36864
	v_cvt_pk_bf16_f32 v48, v51, s0
	ds_write_b16 v185, v48 offset:36864
	v_cvt_pk_bf16_f32 v48, v52, s0
	ds_write_b16 v186, v48 offset:36864
	v_cvt_pk_bf16_f32 v48, v53, s0
	ds_write_b16 v102, v48 offset:39312
	v_cvt_pk_bf16_f32 v48, v54, s0
	ds_write_b16 v102, v48 offset:39584
	v_cvt_pk_bf16_f32 v48, v55, s0
	ds_write_b16 v102, v48 offset:39856
	v_cvt_pk_bf16_f32 v48, v56, s0
	ds_write_b16 v187, v48 offset:36864
	v_cvt_pk_bf16_f32 v48, v57, s0
	ds_write_b16 v102, v48 offset:41488
	v_cvt_pk_bf16_f32 v48, v58, s0
	ds_write_b16 v102, v48 offset:41760
	v_cvt_pk_bf16_f32 v48, v59, s0
	ds_write_b16 v102, v48 offset:42032
	v_cvt_pk_bf16_f32 v48, v60, s0
	ds_write_b16 v188, v48 offset:36864
	v_cvt_pk_bf16_f32 v48, v61, s0
	ds_write_b16 v102, v48 offset:43664
	v_cvt_pk_bf16_f32 v48, v62, s0
	v_cvt_pk_bf16_f32 v32, v32, s0
	ds_write_b16 v102, v48 offset:43936
	v_cvt_pk_bf16_f32 v48, v63, s0
	ds_write_b16 v102, v32 offset:36928
	v_cvt_pk_bf16_f32 v32, v33, s0
	ds_write_b16 v102, v48 offset:44208
	ds_write_b16 v183, v32 offset:36928
	v_cvt_pk_bf16_f32 v32, v34, s0
	ds_write_b16 v184, v32 offset:36928
	v_cvt_pk_bf16_f32 v32, v35, s0
	v_mfma_f32_32x32x16_bf16 v[0:15], v[68:71], v[76:79], v[0:15]
	ds_write_b16 v185, v32 offset:36928
	v_cvt_pk_bf16_f32 v32, v36, s0
	ds_write_b16 v186, v32 offset:36928
	v_cvt_pk_bf16_f32 v32, v37, s0
	ds_write_b16 v102, v32 offset:39376
	v_cvt_pk_bf16_f32 v32, v38, s0
	ds_write_b16 v102, v32 offset:39648
	v_mfma_f32_32x32x16_bf16 v[16:31], v[68:71], v[72:75], v[16:31]
	v_cvt_pk_bf16_f32 v32, v39, s0
	ds_write_b16 v102, v32 offset:39920
	v_cvt_pk_bf16_f32 v32, v40, s0
	ds_write_b16 v187, v32 offset:36928
	v_cvt_pk_bf16_f32 v32, v41, s0
	ds_write_b16 v102, v32 offset:41552
	v_cvt_pk_bf16_f32 v32, v42, s0
	ds_write_b16 v102, v32 offset:41824
	v_cvt_pk_bf16_f32 v32, v43, s0
	ds_write_b16 v102, v32 offset:42096
	v_cvt_pk_bf16_f32 v32, v44, s0
	v_cvt_pk_bf16_f32 v0, v0, s0
	ds_write_b16 v188, v32 offset:36928
	v_cvt_pk_bf16_f32 v16, v16, s0
	ds_write_b16 v102, v0 offset:45632
	v_cvt_pk_bf16_f32 v0, v1, s0
	ds_write_b16 v102, v16 offset:45568
	v_cvt_pk_bf16_f32 v16, v17, s0
	ds_write_b16 v102, v0 offset:45904
	v_cvt_pk_bf16_f32 v0, v2, s0
	ds_write_b16 v102, v16 offset:45840
	v_cvt_pk_bf16_f32 v16, v18, s0
	ds_write_b16 v102, v0 offset:46176
	v_cvt_pk_bf16_f32 v0, v3, s0
	ds_write_b16 v102, v16 offset:46112
	v_cvt_pk_bf16_f32 v16, v19, s0
	ds_write_b16 v102, v0 offset:46448
	v_cvt_pk_bf16_f32 v0, v4, s0
	ds_write_b16 v102, v16 offset:46384
	v_cvt_pk_bf16_f32 v16, v20, s0
	ds_write_b16 v102, v0 offset:47808
	v_cvt_pk_bf16_f32 v0, v5, s0
	ds_write_b16 v102, v16 offset:47744
	v_cvt_pk_bf16_f32 v16, v21, s0
	ds_write_b16 v102, v0 offset:48080
	v_cvt_pk_bf16_f32 v0, v6, s0
	ds_write_b16 v102, v16 offset:48016
	v_cvt_pk_bf16_f32 v16, v22, s0
	ds_write_b16 v102, v0 offset:48352
	v_cvt_pk_bf16_f32 v0, v7, s0
	ds_write_b16 v102, v16 offset:48288
	v_cvt_pk_bf16_f32 v16, v23, s0
	ds_write_b16 v102, v0 offset:48624
	v_cvt_pk_bf16_f32 v0, v8, s0
	ds_write_b16 v102, v16 offset:48560
	v_cvt_pk_bf16_f32 v16, v24, s0
	ds_write_b16 v102, v0 offset:49984
	v_cvt_pk_bf16_f32 v0, v9, s0
	ds_write_b16 v102, v16 offset:49920
	v_cvt_pk_bf16_f32 v16, v25, s0
	ds_write_b16 v102, v0 offset:50256
	v_cvt_pk_bf16_f32 v0, v10, s0
	ds_write_b16 v102, v16 offset:50192
	v_cvt_pk_bf16_f32 v16, v26, s0
	ds_write_b16 v102, v0 offset:50528
	v_cvt_pk_bf16_f32 v0, v11, s0
	ds_write_b16 v102, v16 offset:50464
	v_cvt_pk_bf16_f32 v16, v27, s0
	ds_write_b16 v102, v0 offset:50800
	v_cvt_pk_bf16_f32 v0, v12, s0
	ds_write_b16 v102, v16 offset:50736
	v_cvt_pk_bf16_f32 v16, v28, s0
	ds_write_b16 v102, v0 offset:52160
	v_cvt_pk_bf16_f32 v0, v13, s0
	v_cvt_pk_bf16_f32 v32, v45, s0
	ds_write_b16 v102, v16 offset:52096
	v_cvt_pk_bf16_f32 v16, v29, s0
	ds_write_b16 v102, v0 offset:52432
	v_cvt_pk_bf16_f32 v0, v14, s0
	ds_write_b16 v102, v32 offset:43728
	v_cvt_pk_bf16_f32 v32, v46, s0
	ds_write_b16 v102, v16 offset:52368
	v_cvt_pk_bf16_f32 v16, v30, s0
	ds_write_b16 v102, v0 offset:52704
	v_cvt_pk_bf16_f32 v0, v15, s0
	v_lshl_add_u64 v[4:5], v[146:147], 0, s[38:39]
	ds_write_b16 v102, v32 offset:44000
	v_cvt_pk_bf16_f32 v32, v47, s0
	ds_write_b16 v102, v16 offset:52640
	v_cvt_pk_bf16_f32 v16, v31, s0
	ds_write_b16 v102, v0 offset:52976
	v_lshl_add_u64 v[0:1], v[104:105], 1, v[4:5]
	ds_write_b16 v102, v32 offset:44272
	ds_write_b16 v102, v16 offset:52912
	global_load_dwordx4 v[64:67], v[0:1], off
	v_lshl_add_u64 v[0:1], v[108:109], 1, v[4:5]
	global_load_dwordx4 v[68:71], v[0:1], off
	v_lshl_add_u64 v[0:1], v[112:113], 1, v[4:5]
	global_load_dwordx4 v[72:75], v[0:1], off
	v_lshl_add_u64 v[0:1], v[116:117], 1, v[4:5]
	global_load_dwordx4 v[76:79], v[0:1], off
	v_lshl_add_u64 v[0:1], v[120:121], 1, v[4:5]
	global_load_dwordx4 v[80:83], v[0:1], off
	v_lshl_add_u64 v[0:1], v[124:125], 1, v[4:5]
	global_load_dwordx4 v[84:87], v[0:1], off
	v_lshl_add_u64 v[0:1], v[128:129], 1, v[4:5]
	global_load_dwordx4 v[88:91], v[0:1], off
	v_lshl_add_u64 v[0:1], v[132:133], 1, v[4:5]
	global_load_dwordx4 v[92:95], v[0:1], off
	s_waitcnt lgkmcnt(0)
	s_barrier
; DEV f32x16 mfma32(bf16x8 a, bf16x8 b, f32x16 c) { return __builtin_amdgcn_mfma_f32_32x32x16_bf16(a, b, c, 0, 0, 0); }
; __device__ void peer_q_topk_item(const Params& P, int l, int item, char* smem) {
;     ...
;     __syncthreads();
;     {
;       const bf16_t* skg = P.SK + (size_t)((l * 2 + c) * 128) * 128;
; #pragma unroll
;       for (int k = 0; k < 8; ++k) {
;         const int ch = tid + 256 * k;
;         const int row = ch >> 4, c8 = (ch & 15) * 8;
;         *(uint4*)(As + row * 136 + c8) = *(const uint4*)(skg + row * 128 + c8);
;       }
;     }
;     __syncthreads();
;     unsigned Lc[16];
;     {
;       f32x16 sa[4];
; #pragma unroll
;       for (int m4 = 0; m4 < 4; ++m4)
; #pragma unroll
;         for (int i = 0; i < 16; ++i) sa[m4][i] = 0.f;
;       const bf16_t* qrow = Qs + (w * 32 + q) * 136 + hk * 8;
;       const bf16_t* sk = As + q * 136 + hk * 8;
; #pragma unroll
;       for (int ks = 0; ks < 8; ++ks) {
;         const bf16x8 bq = *(const bf16x8*)(qrow + ks * 16);
; #pragma unroll
;         for (int m4 = 0; m4 < 4; ++m4) {
;           const bf16x8 a = *(const bf16x8*)(sk + (m4 * 32) * 136 + ks * 16);
;           sa[m4] = mfma32(a, bq, sa[m4]);
;         }
;       }
	s_movk_i32 s39, 0x7f
	s_movk_i32 s38, 0x5f
	s_waitcnt vmcnt(7)
	ds_write_b128 v106, v[64:67]
	s_waitcnt vmcnt(6)
	ds_write_b128 v110, v[68:71]
	s_waitcnt vmcnt(5)
	ds_write_b128 v114, v[72:75]
	s_waitcnt vmcnt(4)
	ds_write_b128 v118, v[76:79]
	s_waitcnt vmcnt(3)
	ds_write_b128 v122, v[80:83]
	s_waitcnt vmcnt(2)
	ds_write_b128 v126, v[84:87]
	s_waitcnt vmcnt(1)
	ds_write_b128 v130, v[88:91]
	s_waitcnt vmcnt(0)
	ds_write_b128 v134, v[92:95]
	s_waitcnt lgkmcnt(0)
	s_barrier
	ds_read_b128 v[0:3], v100 offset:36864
	ds_read_b128 v[64:67], v100 offset:36896
	ds_read_b128 v[4:7], v160
	ds_read_b128 v[68:71], v160 offset:32
	s_waitcnt lgkmcnt(1)
	v_mfma_f32_32x32x16_bf16 v[48:63], v[4:7], v[0:3], 0
	ds_read_b128 v[4:7], v160 offset:8704
	s_waitcnt lgkmcnt(1)
	v_mfma_f32_32x32x16_bf16 v[48:63], v[68:71], v[64:67], v[48:63]
	ds_read_b128 v[68:71], v160 offset:8736
	s_waitcnt lgkmcnt(1)
	v_mfma_f32_32x32x16_bf16 v[32:47], v[4:7], v[0:3], 0
	ds_read_b128 v[4:7], v160 offset:17408
	s_waitcnt lgkmcnt(1)
	v_mfma_f32_32x32x16_bf16 v[32:47], v[68:71], v[64:67], v[32:47]
	ds_read_b128 v[68:71], v160 offset:17440
	s_waitcnt lgkmcnt(1)
	v_mfma_f32_32x32x16_bf16 v[16:31], v[4:7], v[0:3], 0
	ds_read_b128 v[4:7], v160 offset:26112
	s_waitcnt lgkmcnt(1)
	v_mfma_f32_32x32x16_bf16 v[16:31], v[68:71], v[64:67], v[16:31]
	ds_read_b128 v[68:71], v160 offset:26144
	s_waitcnt lgkmcnt(1)
	v_mfma_f32_32x32x16_bf16 v[0:15], v[4:7], v[0:3], 0
	s_waitcnt lgkmcnt(0)
	v_mfma_f32_32x32x16_bf16 v[0:15], v[68:71], v[64:67], v[0:15]
	ds_read_b128 v[64:67], v100 offset:36928
	ds_read_b128 v[68:71], v160 offset:64
	ds_read_b128 v[72:75], v160 offset:8768
	ds_read_b128 v[80:83], v160 offset:17472
	ds_read_b128 v[84:87], v160 offset:26176
	ds_read_b128 v[76:79], v100 offset:36960
	s_waitcnt lgkmcnt(4)
	v_mfma_f32_32x32x16_bf16 v[48:63], v[68:71], v[64:67], v[48:63]
	ds_read_b128 v[68:71], v160 offset:96
	s_waitcnt lgkmcnt(4)
	v_mfma_f32_32x32x16_bf16 v[32:47], v[72:75], v[64:67], v[32:47]
	ds_read_b128 v[72:75], v160 offset:8800
	s_waitcnt lgkmcnt(4)
	v_mfma_f32_32x32x16_bf16 v[16:31], v[80:83], v[64:67], v[16:31]
	ds_read_b128 v[80:83], v160 offset:17504
	s_waitcnt lgkmcnt(4)
	v_mfma_f32_32x32x16_bf16 v[0:15], v[84:87], v[64:67], v[0:15]
	ds_read_b128 v[84:87], v160 offset:26208
	ds_read_b128 v[64:67], v100 offset:36992
	s_waitcnt lgkmcnt(4)
	v_mfma_f32_32x32x16_bf16 v[48:63], v[68:71], v[76:79], v[48:63]
	ds_read_b128 v[68:71], v160 offset:128
	s_waitcnt lgkmcnt(4)
	v_mfma_f32_32x32x16_bf16 v[32:47], v[72:75], v[76:79], v[32:47]
	ds_read_b128 v[72:75], v160 offset:8832
	s_waitcnt lgkmcnt(4)
	v_mfma_f32_32x32x16_bf16 v[16:31], v[80:83], v[76:79], v[16:31]
	ds_read_b128 v[80:83], v160 offset:17536
	s_waitcnt lgkmcnt(4)
	v_mfma_f32_32x32x16_bf16 v[0:15], v[84:87], v[76:79], v[0:15]
	ds_read_b128 v[84:87], v160 offset:26240
	ds_read_b128 v[76:79], v100 offset:37024
	s_waitcnt lgkmcnt(4)
	v_mfma_f32_32x32x16_bf16 v[48:63], v[68:71], v[64:67], v[48:63]
	ds_read_b128 v[68:71], v160 offset:160
	s_waitcnt lgkmcnt(4)
	v_mfma_f32_32x32x16_bf16 v[32:47], v[72:75], v[64:67], v[32:47]
	ds_read_b128 v[72:75], v160 offset:8864
	s_waitcnt lgkmcnt(4)
	v_mfma_f32_32x32x16_bf16 v[16:31], v[80:83], v[64:67], v[16:31]
	ds_read_b128 v[80:83], v160 offset:17568
	s_waitcnt lgkmcnt(4)
	v_mfma_f32_32x32x16_bf16 v[0:15], v[84:87], v[64:67], v[0:15]
	ds_read_b128 v[84:87], v160 offset:26272
	ds_read_b128 v[64:67], v100 offset:37056
	s_waitcnt lgkmcnt(4)
	v_mfma_f32_32x32x16_bf16 v[48:63], v[68:71], v[76:79], v[48:63]
	ds_read_b128 v[68:71], v160 offset:192
	s_waitcnt lgkmcnt(4)
	v_mfma_f32_32x32x16_bf16 v[32:47], v[72:75], v[76:79], v[32:47]
	ds_read_b128 v[72:75], v160 offset:8896
	s_waitcnt lgkmcnt(4)
	v_mfma_f32_32x32x16_bf16 v[16:31], v[80:83], v[76:79], v[16:31]
	ds_read_b128 v[80:83], v160 offset:17600
	s_waitcnt lgkmcnt(4)
	v_mfma_f32_32x32x16_bf16 v[0:15], v[84:87], v[76:79], v[0:15]
	ds_read_b128 v[84:87], v160 offset:26304
	ds_read_b128 v[76:79], v100 offset:37088
	s_waitcnt lgkmcnt(4)
	v_mfma_f32_32x32x16_bf16 v[48:63], v[68:71], v[64:67], v[48:63]
	ds_read_b128 v[68:71], v160 offset:224
	s_waitcnt lgkmcnt(4)
	v_mfma_f32_32x32x16_bf16 v[32:47], v[72:75], v[64:67], v[32:47]
	ds_read_b128 v[72:75], v160 offset:8928
	s_waitcnt lgkmcnt(4)
	v_mfma_f32_32x32x16_bf16 v[16:31], v[80:83], v[64:67], v[16:31]
	ds_read_b128 v[80:83], v160 offset:17632
	s_waitcnt lgkmcnt(4)
	v_mfma_f32_32x32x16_bf16 v[0:15], v[84:87], v[64:67], v[0:15]
	ds_read_b128 v[84:87], v160 offset:26336
	s_waitcnt lgkmcnt(3)
	v_mfma_f32_32x32x16_bf16 v[48:63], v[68:71], v[76:79], v[48:63]
	s_waitcnt lgkmcnt(2)
	v_mfma_f32_32x32x16_bf16 v[32:47], v[72:75], v[76:79], v[32:47]
	s_waitcnt lgkmcnt(1)
	v_mfma_f32_32x32x16_bf16 v[16:31], v[80:83], v[76:79], v[16:31]
	s_waitcnt lgkmcnt(0)
; DEV unsigned fkey(float v) { const unsigned u = __float_as_uint(v); return (u & 0x80000000u) ? ~u : (u | 0x80000000u); }
; __device__ void peer_q_topk_item(const Params& P, int l, int item, char* smem) {
;     ...
;       unsigned G1[16], G2[16], G3[16];
; #pragma unroll
;       for (int i = 0; i < 16; ++i) {
;         const int kb0 = (i & 3) + 8 * (i >> 2) + 4 * hk;
;         Lc[i] = (fkey(sa[0][i]) & ~0x7Fu) | (unsigned)(127 - kb0);
;         G1[i] = (fkey(sa[1][i]) & ~0x7Fu) | (unsigned)(127 - (32 + kb0));
;         G2[i] = (fkey(sa[2][i]) & ~0x7Fu) | (unsigned)(127 - (64 + kb0));
;         G3[i] = (fkey(sa[3][i]) & ~0x7Fu) | (unsigned)(127 - (96 + kb0));
;       }
	v_mfma_f32_32x32x16_bf16 v[0:15], v[84:87], v[76:79], v[0:15]
	s_nop 7
	s_mov_b32 vcc_lo, 0x80000000
	v_ashrrev_i32_e32 v64, 31, v48
	v_bitop3_b32 v48, v48, v64, vcc_lo bitop3:0x1e
	v_ashrrev_i32_e32 v64, 31, v32
	v_and_b32_e32 v48, 0xffffff80, v48
	v_bitop3_b32 v48, v48, s39, v159 bitop3:0x36
	v_bitop3_b32 v32, v32, v64, vcc_lo bitop3:0x1e
	v_ashrrev_i32_e32 v64, 31, v16
	v_and_b32_e32 v32, 0xffffff80, v32
	v_bitop3_b32 v32, v32, s38, v159 bitop3:0x36
	v_bitop3_b32 v16, v16, v64, vcc_lo bitop3:0x1e
	v_ashrrev_i32_e32 v64, 31, v0
	v_and_b32_e32 v16, 0xffffff80, v16
	v_bitop3_b32 v16, v16, 63, v159 bitop3:0x36
	v_bitop3_b32 v0, v0, v64, vcc_lo bitop3:0x1e
	v_ashrrev_i32_e32 v64, 31, v49
	v_and_b32_e32 v0, 0xffffff80, v0
	v_bitop3_b32 v0, v0, 31, v159 bitop3:0x36
	v_bitop3_b32 v49, v49, v64, vcc_lo bitop3:0x1e
	v_ashrrev_i32_e32 v64, 31, v33
	v_and_b32_e32 v49, 0xffffff80, v49
	v_bitop3_b32 v49, v49, s39, v163 bitop3:0x36
	v_bitop3_b32 v33, v33, v64, vcc_lo bitop3:0x1e
	v_ashrrev_i32_e32 v64, 31, v17
	v_and_b32_e32 v33, 0xffffff80, v33
	v_bitop3_b32 v33, v33, s38, v163 bitop3:0x36
	v_bitop3_b32 v17, v17, v64, vcc_lo bitop3:0x1e
	v_ashrrev_i32_e32 v64, 31, v1
	v_and_b32_e32 v17, 0xffffff80, v17
	v_bitop3_b32 v17, v17, 63, v163 bitop3:0x36
	v_bitop3_b32 v1, v1, v64, vcc_lo bitop3:0x1e
	v_ashrrev_i32_e32 v64, 31, v50
	v_and_b32_e32 v1, 0xffffff80, v1
	v_bitop3_b32 v1, v1, 31, v163 bitop3:0x36
	v_bitop3_b32 v50, v50, v64, vcc_lo bitop3:0x1e
	v_ashrrev_i32_e32 v64, 31, v34
	v_and_b32_e32 v50, 0xffffff80, v50
	v_bitop3_b32 v50, v50, s39, v164 bitop3:0x36
	v_bitop3_b32 v34, v34, v64, vcc_lo bitop3:0x1e
	v_ashrrev_i32_e32 v64, 31, v18
	v_and_b32_e32 v34, 0xffffff80, v34
	v_bitop3_b32 v34, v34, s38, v164 bitop3:0x36
	v_bitop3_b32 v18, v18, v64, vcc_lo bitop3:0x1e
	v_ashrrev_i32_e32 v64, 31, v2
	v_and_b32_e32 v18, 0xffffff80, v18
	v_bitop3_b32 v18, v18, 63, v164 bitop3:0x36
	v_bitop3_b32 v2, v2, v64, vcc_lo bitop3:0x1e
	v_ashrrev_i32_e32 v64, 31, v51
	v_and_b32_e32 v2, 0xffffff80, v2
	v_bitop3_b32 v2, v2, 31, v164 bitop3:0x36
	v_bitop3_b32 v51, v51, v64, vcc_lo bitop3:0x1e
	v_ashrrev_i32_e32 v64, 31, v35
	v_and_b32_e32 v51, 0xffffff80, v51
	v_bitop3_b32 v51, v51, s39, v166 bitop3:0x36
	v_bitop3_b32 v35, v35, v64, vcc_lo bitop3:0x1e
	v_ashrrev_i32_e32 v64, 31, v19
	v_and_b32_e32 v35, 0xffffff80, v35
	v_bitop3_b32 v35, v35, s38, v166 bitop3:0x36
	v_bitop3_b32 v19, v19, v64, vcc_lo bitop3:0x1e
	v_ashrrev_i32_e32 v64, 31, v3
	v_and_b32_e32 v19, 0xffffff80, v19
	v_bitop3_b32 v19, v19, 63, v166 bitop3:0x36
	v_bitop3_b32 v3, v3, v64, vcc_lo bitop3:0x1e
	v_ashrrev_i32_e32 v64, 31, v52
	v_and_b32_e32 v3, 0xffffff80, v3
	v_bitop3_b32 v3, v3, 31, v166 bitop3:0x36
	v_bitop3_b32 v52, v52, v64, vcc_lo bitop3:0x1e
	v_ashrrev_i32_e32 v64, 31, v36
	v_and_b32_e32 v52, 0xffffff80, v52
	v_bitop3_b32 v52, v52, s39, v167 bitop3:0x36
	v_bitop3_b32 v36, v36, v64, vcc_lo bitop3:0x1e
	v_ashrrev_i32_e32 v64, 31, v20
	v_and_b32_e32 v36, 0xffffff80, v36
	v_bitop3_b32 v36, v36, s38, v167 bitop3:0x36
	v_bitop3_b32 v20, v20, v64, vcc_lo bitop3:0x1e
	v_ashrrev_i32_e32 v64, 31, v4
	v_and_b32_e32 v20, 0xffffff80, v20
	v_bitop3_b32 v20, v20, 63, v167 bitop3:0x36
	v_bitop3_b32 v4, v4, v64, vcc_lo bitop3:0x1e
	v_ashrrev_i32_e32 v64, 31, v53
	v_and_b32_e32 v4, 0xffffff80, v4
	v_bitop3_b32 v4, v4, 31, v167 bitop3:0x36
	v_bitop3_b32 v53, v53, v64, vcc_lo bitop3:0x1e
	v_ashrrev_i32_e32 v64, 31, v37
	v_and_b32_e32 v53, 0xffffff80, v53
	v_bitop3_b32 v53, v53, s39, v171 bitop3:0x36
	v_bitop3_b32 v37, v37, v64, vcc_lo bitop3:0x1e
	v_ashrrev_i32_e32 v64, 31, v21
	v_and_b32_e32 v37, 0xffffff80, v37
	v_bitop3_b32 v37, v37, s38, v171 bitop3:0x36
	v_bitop3_b32 v21, v21, v64, vcc_lo bitop3:0x1e
	v_ashrrev_i32_e32 v64, 31, v5
	v_and_b32_e32 v21, 0xffffff80, v21
	v_bitop3_b32 v21, v21, 63, v171 bitop3:0x36
	v_bitop3_b32 v5, v5, v64, vcc_lo bitop3:0x1e
	v_ashrrev_i32_e32 v64, 31, v54
	v_and_b32_e32 v5, 0xffffff80, v5
	v_bitop3_b32 v5, v5, 31, v171 bitop3:0x36
	v_bitop3_b32 v54, v54, v64, vcc_lo bitop3:0x1e
	v_ashrrev_i32_e32 v64, 31, v38
	v_and_b32_e32 v54, 0xffffff80, v54
	v_bitop3_b32 v54, v54, s39, v172 bitop3:0x36
	v_bitop3_b32 v38, v38, v64, vcc_lo bitop3:0x1e
	v_ashrrev_i32_e32 v64, 31, v22
	v_and_b32_e32 v38, 0xffffff80, v38
	v_bitop3_b32 v38, v38, s38, v172 bitop3:0x36
	v_bitop3_b32 v22, v22, v64, vcc_lo bitop3:0x1e
	v_ashrrev_i32_e32 v64, 31, v6
	v_and_b32_e32 v22, 0xffffff80, v22
	v_bitop3_b32 v22, v22, 63, v172 bitop3:0x36
	v_bitop3_b32 v6, v6, v64, vcc_lo bitop3:0x1e
	v_ashrrev_i32_e32 v64, 31, v55
	v_and_b32_e32 v6, 0xffffff80, v6
	v_bitop3_b32 v6, v6, 31, v172 bitop3:0x36
	v_bitop3_b32 v55, v55, v64, vcc_lo bitop3:0x1e
	v_ashrrev_i32_e32 v64, 31, v39
	v_and_b32_e32 v55, 0xffffff80, v55
	v_bitop3_b32 v55, v55, s39, v173 bitop3:0x36
	v_bitop3_b32 v39, v39, v64, vcc_lo bitop3:0x1e
	v_ashrrev_i32_e32 v64, 31, v23
	v_and_b32_e32 v39, 0xffffff80, v39
	v_bitop3_b32 v39, v39, s38, v173 bitop3:0x36
	v_bitop3_b32 v23, v23, v64, vcc_lo bitop3:0x1e
	v_ashrrev_i32_e32 v64, 31, v7
	v_and_b32_e32 v23, 0xffffff80, v23
	v_bitop3_b32 v23, v23, 63, v173 bitop3:0x36
	v_bitop3_b32 v7, v7, v64, vcc_lo bitop3:0x1e
	v_ashrrev_i32_e32 v64, 31, v56
	v_and_b32_e32 v7, 0xffffff80, v7
	v_bitop3_b32 v7, v7, 31, v173 bitop3:0x36
	v_bitop3_b32 v56, v56, v64, vcc_lo bitop3:0x1e
	v_ashrrev_i32_e32 v64, 31, v40
	v_and_b32_e32 v56, 0xffffff80, v56
	v_bitop3_b32 v56, v56, s39, v169 bitop3:0x36
	v_bitop3_b32 v40, v40, v64, vcc_lo bitop3:0x1e
	v_ashrrev_i32_e32 v64, 31, v24
	v_and_b32_e32 v40, 0xffffff80, v40
	v_bitop3_b32 v40, v40, s38, v169 bitop3:0x36
	v_bitop3_b32 v24, v24, v64, vcc_lo bitop3:0x1e
	v_ashrrev_i32_e32 v64, 31, v8
; DEV unsigned fkey(float v) { const unsigned u = __float_as_uint(v); return (u & 0x80000000u) ? ~u : (u | 0x80000000u); }
; DEV void sort16_desc(unsigned (&x)[16]) {
; #pragma unroll
;   for (int k = 2; k <= 16; k <<= 1)
; #pragma unroll
;     for (int j = k >> 1; j > 0; j >>= 1)
; #pragma unroll
;       for (int i = 0; i < 16; ++i) {
;         const int p = i ^ j;
;         if (p > i) {
;           if ((i & k) == 0) { TK_CE(x[i], x[p]); } else { TK_CE(x[p], x[i]); }
;         }
;       }
; }
; __device__ void peer_q_topk_item(const Params& P, int l, int item, char* smem) {
;     ...
;       for (int i = 0; i < 16; ++i) {
;         const int kb0 = (i & 3) + 8 * (i >> 2) + 4 * hk;
;         Lc[i] = (fkey(sa[0][i]) & ~0x7Fu) | (unsigned)(127 - kb0);
;         G1[i] = (fkey(sa[1][i]) & ~0x7Fu) | (unsigned)(127 - (32 + kb0));
;         G2[i] = (fkey(sa[2][i]) & ~0x7Fu) | (unsigned)(127 - (64 + kb0));
;         G3[i] = (fkey(sa[3][i]) & ~0x7Fu) | (unsigned)(127 - (96 + kb0));
;       }
	v_and_b32_e32 v24, 0xffffff80, v24
	v_bitop3_b32 v24, v24, 63, v169 bitop3:0x36
	v_bitop3_b32 v8, v8, v64, vcc_lo bitop3:0x1e
	v_ashrrev_i32_e32 v64, 31, v57
	v_and_b32_e32 v8, 0xffffff80, v8
	v_bitop3_b32 v8, v8, 31, v169 bitop3:0x36
	v_bitop3_b32 v57, v57, v64, vcc_lo bitop3:0x1e
	v_ashrrev_i32_e32 v64, 31, v41
	v_and_b32_e32 v57, 0xffffff80, v57
	v_bitop3_b32 v57, v57, s39, v174 bitop3:0x36
	v_bitop3_b32 v41, v41, v64, vcc_lo bitop3:0x1e
	v_ashrrev_i32_e32 v64, 31, v25
	v_and_b32_e32 v41, 0xffffff80, v41
	v_bitop3_b32 v41, v41, s38, v174 bitop3:0x36
	v_bitop3_b32 v25, v25, v64, vcc_lo bitop3:0x1e
	v_ashrrev_i32_e32 v64, 31, v9
	v_and_b32_e32 v25, 0xffffff80, v25
	v_bitop3_b32 v25, v25, 63, v174 bitop3:0x36
	v_bitop3_b32 v9, v9, v64, vcc_lo bitop3:0x1e
	v_ashrrev_i32_e32 v64, 31, v58
	v_and_b32_e32 v9, 0xffffff80, v9
	v_bitop3_b32 v9, v9, 31, v174 bitop3:0x36
	v_bitop3_b32 v58, v58, v64, vcc_lo bitop3:0x1e
	v_ashrrev_i32_e32 v64, 31, v42
	v_and_b32_e32 v58, 0xffffff80, v58
	v_bitop3_b32 v58, v58, s39, v175 bitop3:0x36
	v_bitop3_b32 v42, v42, v64, vcc_lo bitop3:0x1e
	v_ashrrev_i32_e32 v64, 31, v26
	v_and_b32_e32 v42, 0xffffff80, v42
	v_bitop3_b32 v42, v42, s38, v175 bitop3:0x36
	v_bitop3_b32 v26, v26, v64, vcc_lo bitop3:0x1e
	v_ashrrev_i32_e32 v64, 31, v10
	v_and_b32_e32 v26, 0xffffff80, v26
	v_bitop3_b32 v26, v26, 63, v175 bitop3:0x36
	v_bitop3_b32 v10, v10, v64, vcc_lo bitop3:0x1e
	v_ashrrev_i32_e32 v64, 31, v59
	v_and_b32_e32 v10, 0xffffff80, v10
	v_bitop3_b32 v10, v10, 31, v175 bitop3:0x36
	v_bitop3_b32 v59, v59, v64, vcc_lo bitop3:0x1e
	v_ashrrev_i32_e32 v64, 31, v43
	v_and_b32_e32 v59, 0xffffff80, v59
	v_bitop3_b32 v59, v59, s39, v179 bitop3:0x36
	v_bitop3_b32 v43, v43, v64, vcc_lo bitop3:0x1e
	v_ashrrev_i32_e32 v64, 31, v27
	v_and_b32_e32 v43, 0xffffff80, v43
	v_bitop3_b32 v43, v43, s38, v179 bitop3:0x36
	v_bitop3_b32 v27, v27, v64, vcc_lo bitop3:0x1e
	v_ashrrev_i32_e32 v64, 31, v11
	v_and_b32_e32 v27, 0xffffff80, v27
	v_bitop3_b32 v27, v27, 63, v179 bitop3:0x36
	v_bitop3_b32 v11, v11, v64, vcc_lo bitop3:0x1e
	v_ashrrev_i32_e32 v64, 31, v60
	v_and_b32_e32 v11, 0xffffff80, v11
	v_bitop3_b32 v11, v11, 31, v179 bitop3:0x36
	v_bitop3_b32 v60, v60, v64, vcc_lo bitop3:0x1e
	v_ashrrev_i32_e32 v64, 31, v44
	v_and_b32_e32 v60, 0xffffff80, v60
	v_bitop3_b32 v60, v60, s39, v170 bitop3:0x36
	v_bitop3_b32 v44, v44, v64, vcc_lo bitop3:0x1e
	v_ashrrev_i32_e32 v64, 31, v28
	v_and_b32_e32 v44, 0xffffff80, v44
	v_bitop3_b32 v44, v44, s38, v170 bitop3:0x36
	v_bitop3_b32 v28, v28, v64, vcc_lo bitop3:0x1e
	v_ashrrev_i32_e32 v64, 31, v12
	v_and_b32_e32 v28, 0xffffff80, v28
	v_bitop3_b32 v28, v28, 63, v170 bitop3:0x36
	v_bitop3_b32 v12, v12, v64, vcc_lo bitop3:0x1e
	v_ashrrev_i32_e32 v64, 31, v61
	v_and_b32_e32 v12, 0xffffff80, v12
	v_bitop3_b32 v12, v12, 31, v170 bitop3:0x36
	v_bitop3_b32 v61, v61, v64, vcc_lo bitop3:0x1e
	v_ashrrev_i32_e32 v64, 31, v45
	v_and_b32_e32 v61, 0xffffff80, v61
	v_bitop3_b32 v61, v61, s39, v180 bitop3:0x36
	v_bitop3_b32 v45, v45, v64, vcc_lo bitop3:0x1e
	v_ashrrev_i32_e32 v64, 31, v29
	v_and_b32_e32 v45, 0xffffff80, v45
	v_bitop3_b32 v45, v45, s38, v180 bitop3:0x36
	v_bitop3_b32 v29, v29, v64, vcc_lo bitop3:0x1e
	v_ashrrev_i32_e32 v64, 31, v13
	v_and_b32_e32 v29, 0xffffff80, v29
	v_bitop3_b32 v29, v29, 63, v180 bitop3:0x36
	v_bitop3_b32 v13, v13, v64, vcc_lo bitop3:0x1e
	v_ashrrev_i32_e32 v64, 31, v62
	v_and_b32_e32 v13, 0xffffff80, v13
	v_bitop3_b32 v13, v13, 31, v180 bitop3:0x36
	v_bitop3_b32 v62, v62, v64, vcc_lo bitop3:0x1e
	v_ashrrev_i32_e32 v64, 31, v46
	v_and_b32_e32 v62, 0xffffff80, v62
	v_bitop3_b32 v62, v62, s39, v181 bitop3:0x36
	v_bitop3_b32 v46, v46, v64, vcc_lo bitop3:0x1e
	v_ashrrev_i32_e32 v64, 31, v30
	v_and_b32_e32 v46, 0xffffff80, v46
	v_bitop3_b32 v46, v46, s38, v181 bitop3:0x36
	v_bitop3_b32 v30, v30, v64, vcc_lo bitop3:0x1e
	v_ashrrev_i32_e32 v64, 31, v14
	v_and_b32_e32 v30, 0xffffff80, v30
	v_bitop3_b32 v30, v30, 63, v181 bitop3:0x36
	v_bitop3_b32 v14, v14, v64, vcc_lo bitop3:0x1e
	v_ashrrev_i32_e32 v64, 31, v63
	v_and_b32_e32 v14, 0xffffff80, v14
	v_bitop3_b32 v14, v14, 31, v181 bitop3:0x36
	v_bitop3_b32 v63, v63, v64, vcc_lo bitop3:0x1e
	v_ashrrev_i32_e32 v64, 31, v47
	v_and_b32_e32 v63, 0xffffff80, v63
	v_bitop3_b32 v63, v63, s39, v182 bitop3:0x36
	v_bitop3_b32 v47, v47, v64, vcc_lo bitop3:0x1e
	v_ashrrev_i32_e32 v64, 31, v31
	v_and_b32_e32 v47, 0xffffff80, v47
	v_bitop3_b32 v47, v47, s38, v182 bitop3:0x36
	v_bitop3_b32 v31, v31, v64, vcc_lo bitop3:0x1e
	v_ashrrev_i32_e32 v64, 31, v15
	v_and_b32_e32 v31, 0xffffff80, v31
	v_bitop3_b32 v31, v31, 63, v182 bitop3:0x36
	v_bitop3_b32 v15, v15, v64, vcc_lo bitop3:0x1e
	v_and_b32_e32 v15, 0xffffff80, v15
	v_bitop3_b32 v15, v15, 31, v182 bitop3:0x36
	v_max_u32_e32 v64, v48, v49
	v_min_u32_e32 v48, v48, v49
	v_max_u32_e32 v49, v51, v50
	v_min_u32_e32 v50, v51, v50
	v_max_u32_e32 v51, v52, v53
	v_min_u32_e32 v52, v52, v53
	v_max_u32_e32 v53, v55, v54
	v_min_u32_e32 v54, v55, v54
	v_max_u32_e32 v55, v56, v57
	v_min_u32_e32 v56, v56, v57
	v_max_u32_e32 v57, v59, v58
	v_min_u32_e32 v58, v59, v58
	v_max_u32_e32 v59, v60, v61
	v_min_u32_e32 v60, v60, v61
	v_max_u32_e32 v61, v63, v62
	v_min_u32_e32 v62, v63, v62
	v_max_u32_e32 v72, v32, v33
	v_min_u32_e32 v32, v32, v33
	v_max_u32_e32 v33, v35, v34
	v_min_u32_e32 v34, v35, v34
	v_max_u32_e32 v35, v36, v37
	v_min_u32_e32 v36, v36, v37
	v_max_u32_e32 v37, v39, v38
	v_min_u32_e32 v38, v39, v38
	v_max_u32_e32 v39, v40, v41
	v_min_u32_e32 v40, v40, v41
	v_max_u32_e32 v41, v43, v42
	v_min_u32_e32 v42, v43, v42
	v_max_u32_e32 v43, v44, v45
	v_min_u32_e32 v44, v44, v45
	v_max_u32_e32 v45, v47, v46
	v_min_u32_e32 v46, v47, v46
; DEV void sort16_desc(unsigned (&x)[16]) {
; #pragma unroll
;   for (int k = 2; k <= 16; k <<= 1)
; #pragma unroll
;     for (int j = k >> 1; j > 0; j >>= 1)
; #pragma unroll
;       for (int i = 0; i < 16; ++i) {
;         const int p = i ^ j;
;         if (p > i) {
;           if ((i & k) == 0) { TK_CE(x[i], x[p]); } else { TK_CE(x[p], x[i]); }
;         }
;       }
; }
	v_max_u32_e32 v80, v16, v17
	v_min_u32_e32 v16, v16, v17
	v_max_u32_e32 v17, v19, v18
	v_min_u32_e32 v18, v19, v18
	v_max_u32_e32 v19, v20, v21
	v_min_u32_e32 v20, v20, v21
	v_max_u32_e32 v21, v23, v22
	v_min_u32_e32 v22, v23, v22
	v_max_u32_e32 v23, v24, v25
	v_min_u32_e32 v24, v24, v25
	v_max_u32_e32 v25, v27, v26
	v_min_u32_e32 v26, v27, v26
	v_max_u32_e32 v27, v28, v29
	v_min_u32_e32 v28, v28, v29
	v_max_u32_e32 v29, v31, v30
	v_min_u32_e32 v30, v31, v30
	v_max_u32_e32 v88, v0, v1
	v_min_u32_e32 v0, v0, v1
	v_max_u32_e32 v1, v3, v2
	v_min_u32_e32 v2, v3, v2
	v_max_u32_e32 v3, v4, v5
	v_min_u32_e32 v4, v4, v5
	v_max_u32_e32 v5, v7, v6
	v_min_u32_e32 v6, v7, v6
	v_max_u32_e32 v7, v8, v9
	v_min_u32_e32 v8, v8, v9
	v_max_u32_e32 v9, v11, v10
	v_min_u32_e32 v10, v11, v10
	v_max_u32_e32 v11, v12, v13
	v_min_u32_e32 v12, v12, v13
	v_max_u32_e32 v13, v15, v14
	v_min_u32_e32 v14, v15, v14
	v_max_u32_e32 v63, v64, v50
	v_min_u32_e32 v50, v64, v50
	v_max_u32_e32 v64, v48, v49
	v_min_u32_e32 v48, v48, v49
	v_max_u32_e32 v49, v54, v51
	v_min_u32_e32 v51, v54, v51
	v_max_u32_e32 v54, v53, v52
	v_min_u32_e32 v52, v53, v52
	v_max_u32_e32 v53, v55, v58
	v_min_u32_e32 v55, v55, v58
	v_max_u32_e32 v58, v56, v57
	v_min_u32_e32 v56, v56, v57
	v_max_u32_e32 v57, v62, v59
	v_min_u32_e32 v59, v62, v59
	v_max_u32_e32 v62, v61, v60
	v_min_u32_e32 v60, v61, v60
	v_max_u32_e32 v47, v72, v34
	v_min_u32_e32 v34, v72, v34
	v_max_u32_e32 v72, v32, v33
	v_min_u32_e32 v32, v32, v33
	v_max_u32_e32 v33, v38, v35
	v_min_u32_e32 v35, v38, v35
	v_max_u32_e32 v38, v37, v36
	v_min_u32_e32 v36, v37, v36
	v_max_u32_e32 v37, v39, v42
	v_min_u32_e32 v39, v39, v42
	v_max_u32_e32 v42, v40, v41
	v_min_u32_e32 v40, v40, v41
	v_max_u32_e32 v41, v46, v43
	v_min_u32_e32 v43, v46, v43
	v_max_u32_e32 v46, v45, v44
	v_min_u32_e32 v44, v45, v44
	v_max_u32_e32 v31, v80, v18
	v_min_u32_e32 v18, v80, v18
	v_max_u32_e32 v80, v16, v17
	v_min_u32_e32 v16, v16, v17
	v_max_u32_e32 v17, v22, v19
	v_min_u32_e32 v19, v22, v19
	v_max_u32_e32 v22, v21, v20
	v_min_u32_e32 v20, v21, v20
	v_max_u32_e32 v21, v23, v26
	v_min_u32_e32 v23, v23, v26
	v_max_u32_e32 v26, v24, v25
	v_min_u32_e32 v24, v24, v25
	v_max_u32_e32 v25, v30, v27
	v_min_u32_e32 v27, v30, v27
	v_max_u32_e32 v30, v29, v28
	v_min_u32_e32 v28, v29, v28
	v_max_u32_e32 v15, v88, v2
	v_min_u32_e32 v2, v88, v2
	v_max_u32_e32 v88, v0, v1
	v_min_u32_e32 v0, v0, v1
	v_max_u32_e32 v1, v6, v3
	v_min_u32_e32 v3, v6, v3
	v_max_u32_e32 v6, v5, v4
	v_min_u32_e32 v4, v5, v4
	v_max_u32_e32 v5, v7, v10
	v_min_u32_e32 v7, v7, v10
	v_max_u32_e32 v10, v8, v9
	v_min_u32_e32 v8, v8, v9
	v_max_u32_e32 v9, v14, v11
	v_min_u32_e32 v11, v14, v11
	v_max_u32_e32 v14, v13, v12
	v_min_u32_e32 v12, v13, v12
	v_max_u32_e32 v61, v63, v64
	v_min_u32_e32 v63, v63, v64
	v_max_u32_e32 v64, v50, v48
	v_min_u32_e32 v48, v50, v48
	v_max_u32_e32 v50, v52, v51
	v_min_u32_e32 v51, v52, v51
	v_max_u32_e32 v52, v54, v49
	v_min_u32_e32 v49, v54, v49
	v_max_u32_e32 v54, v53, v58
	v_min_u32_e32 v53, v53, v58
	v_max_u32_e32 v58, v55, v56
	v_min_u32_e32 v55, v55, v56
	v_max_u32_e32 v56, v60, v59
	v_min_u32_e32 v59, v60, v59
	v_max_u32_e32 v60, v62, v57
	v_min_u32_e32 v57, v62, v57
	v_max_u32_e32 v45, v47, v72
	v_min_u32_e32 v47, v47, v72
	v_max_u32_e32 v72, v34, v32
	v_min_u32_e32 v32, v34, v32
	v_max_u32_e32 v34, v36, v35
	v_min_u32_e32 v35, v36, v35
	v_max_u32_e32 v36, v38, v33
	v_min_u32_e32 v33, v38, v33
	v_max_u32_e32 v38, v37, v42
	v_min_u32_e32 v37, v37, v42
	v_max_u32_e32 v42, v39, v40
	v_min_u32_e32 v39, v39, v40
	v_max_u32_e32 v40, v44, v43
	v_min_u32_e32 v43, v44, v43
	v_max_u32_e32 v44, v46, v41
	v_min_u32_e32 v41, v46, v41
	v_max_u32_e32 v29, v31, v80
	v_min_u32_e32 v31, v31, v80
	v_max_u32_e32 v80, v18, v16
	v_min_u32_e32 v16, v18, v16
	v_max_u32_e32 v18, v20, v19
	v_min_u32_e32 v19, v20, v19
	v_max_u32_e32 v20, v22, v17
	v_min_u32_e32 v17, v22, v17
	v_max_u32_e32 v22, v21, v26
	v_min_u32_e32 v21, v21, v26
	v_max_u32_e32 v26, v23, v24
	v_min_u32_e32 v23, v23, v24
	v_max_u32_e32 v24, v28, v27
	v_min_u32_e32 v27, v28, v27
	v_max_u32_e32 v28, v30, v25
	v_min_u32_e32 v25, v30, v25
	v_max_u32_e32 v13, v15, v88
	v_min_u32_e32 v15, v15, v88
	v_max_u32_e32 v88, v2, v0
	v_min_u32_e32 v0, v2, v0
	v_max_u32_e32 v2, v4, v3
	v_min_u32_e32 v3, v4, v3
	v_max_u32_e32 v4, v6, v1
	v_min_u32_e32 v1, v6, v1
	v_max_u32_e32 v6, v5, v10
	v_min_u32_e32 v5, v5, v10
	v_max_u32_e32 v10, v7, v8
	v_min_u32_e32 v7, v7, v8
	v_max_u32_e32 v8, v12, v11
	v_min_u32_e32 v11, v12, v11
	v_max_u32_e32 v12, v14, v9
	v_min_u32_e32 v9, v14, v9
	v_max_u32_e32 v62, v61, v51
	v_min_u32_e32 v51, v61, v51
	v_max_u32_e32 v61, v63, v50
	v_min_u32_e32 v50, v63, v50
	v_max_u32_e32 v63, v64, v49
	v_min_u32_e32 v49, v64, v49
	v_max_u32_e32 v64, v48, v52
	v_min_u32_e32 v48, v48, v52
	v_max_u32_e32 v52, v59, v54
	v_min_u32_e32 v54, v59, v54
	v_max_u32_e32 v59, v56, v53
	v_min_u32_e32 v53, v56, v53
	v_max_u32_e32 v56, v57, v58
	v_min_u32_e32 v57, v57, v58
	v_max_u32_e32 v58, v60, v55
	v_min_u32_e32 v55, v60, v55
	v_max_u32_e32 v46, v45, v35
	v_min_u32_e32 v35, v45, v35
	v_max_u32_e32 v45, v47, v34
	v_min_u32_e32 v34, v47, v34
	v_max_u32_e32 v47, v72, v33
	v_min_u32_e32 v33, v72, v33
	v_max_u32_e32 v72, v32, v36
	v_min_u32_e32 v32, v32, v36
	v_max_u32_e32 v36, v43, v38
	v_min_u32_e32 v38, v43, v38
	v_max_u32_e32 v43, v40, v37
	v_min_u32_e32 v37, v40, v37
	v_max_u32_e32 v40, v41, v42
	v_min_u32_e32 v41, v41, v42
	v_max_u32_e32 v42, v44, v39
	v_min_u32_e32 v39, v44, v39
	v_max_u32_e32 v30, v29, v19
	v_min_u32_e32 v19, v29, v19
	v_max_u32_e32 v29, v31, v18
	v_min_u32_e32 v18, v31, v18
	v_max_u32_e32 v31, v80, v17
	v_min_u32_e32 v17, v80, v17
; DEV void sort16_desc(unsigned (&x)[16]) {
; #pragma unroll
;   for (int k = 2; k <= 16; k <<= 1)
; #pragma unroll
;     for (int j = k >> 1; j > 0; j >>= 1)
; #pragma unroll
;       for (int i = 0; i < 16; ++i) {
;         const int p = i ^ j;
;         if (p > i) {
;           if ((i & k) == 0) { TK_CE(x[i], x[p]); } else { TK_CE(x[p], x[i]); }
;         }
;       }
; }
	v_max_u32_e32 v80, v16, v20
	v_min_u32_e32 v16, v16, v20
	v_max_u32_e32 v20, v27, v22
	v_min_u32_e32 v22, v27, v22
	v_max_u32_e32 v27, v24, v21
	v_min_u32_e32 v21, v24, v21
	v_max_u32_e32 v24, v25, v26
	v_min_u32_e32 v25, v25, v26
	v_max_u32_e32 v26, v28, v23
	v_min_u32_e32 v23, v28, v23
	v_max_u32_e32 v14, v13, v3
	v_min_u32_e32 v3, v13, v3
	v_max_u32_e32 v13, v15, v2
	v_min_u32_e32 v2, v15, v2
	v_max_u32_e32 v15, v88, v1
	v_min_u32_e32 v1, v88, v1
	v_max_u32_e32 v88, v0, v4
	v_min_u32_e32 v0, v0, v4
	v_max_u32_e32 v4, v11, v6
	v_min_u32_e32 v6, v11, v6
	v_max_u32_e32 v11, v8, v5
	v_min_u32_e32 v5, v8, v5
	v_max_u32_e32 v8, v9, v10
	v_min_u32_e32 v9, v9, v10
	v_max_u32_e32 v10, v12, v7
	v_min_u32_e32 v7, v12, v7
	v_max_u32_e32 v60, v62, v63
	v_min_u32_e32 v62, v62, v63
	v_max_u32_e32 v63, v61, v64
	v_min_u32_e32 v61, v61, v64
	v_max_u32_e32 v64, v51, v49
	v_min_u32_e32 v49, v51, v49
	v_max_u32_e32 v51, v50, v48
	v_min_u32_e32 v48, v50, v48
	v_max_u32_e32 v50, v57, v54
	v_min_u32_e32 v54, v57, v54
	v_max_u32_e32 v57, v55, v53
	v_min_u32_e32 v53, v55, v53
	v_max_u32_e32 v55, v56, v52
	v_min_u32_e32 v52, v56, v52
	v_max_u32_e32 v56, v58, v59
	v_min_u32_e32 v58, v58, v59
	v_max_u32_e32 v44, v46, v47
	v_min_u32_e32 v46, v46, v47
	v_max_u32_e32 v47, v45, v72
	v_min_u32_e32 v45, v45, v72
	v_max_u32_e32 v72, v35, v33
	v_min_u32_e32 v33, v35, v33
	v_max_u32_e32 v35, v34, v32
	v_min_u32_e32 v32, v34, v32
	v_max_u32_e32 v34, v41, v38
	v_min_u32_e32 v38, v41, v38
	v_max_u32_e32 v41, v39, v37
	v_min_u32_e32 v37, v39, v37
	v_max_u32_e32 v39, v40, v36
	v_min_u32_e32 v36, v40, v36
	v_max_u32_e32 v40, v42, v43
	v_min_u32_e32 v42, v42, v43
	v_max_u32_e32 v28, v30, v31
	v_min_u32_e32 v30, v30, v31
	v_max_u32_e32 v31, v29, v80
	v_min_u32_e32 v29, v29, v80
	v_max_u32_e32 v80, v19, v17
	v_min_u32_e32 v17, v19, v17
	v_max_u32_e32 v19, v18, v16
	v_min_u32_e32 v16, v18, v16
	v_max_u32_e32 v18, v25, v22
	v_min_u32_e32 v22, v25, v22
	v_max_u32_e32 v25, v23, v21
	v_min_u32_e32 v21, v23, v21
	v_max_u32_e32 v23, v24, v20
	v_min_u32_e32 v20, v24, v20
	v_max_u32_e32 v24, v26, v27
	v_min_u32_e32 v26, v26, v27
	v_max_u32_e32 v12, v14, v15
	v_min_u32_e32 v14, v14, v15
	v_max_u32_e32 v15, v13, v88
	v_min_u32_e32 v13, v13, v88
	v_max_u32_e32 v88, v3, v1
	v_min_u32_e32 v1, v3, v1
	v_max_u32_e32 v3, v2, v0
	v_min_u32_e32 v0, v2, v0
	v_max_u32_e32 v2, v9, v6
	v_min_u32_e32 v6, v9, v6
	v_max_u32_e32 v9, v7, v5
	v_min_u32_e32 v5, v7, v5
	v_max_u32_e32 v7, v8, v4
	v_min_u32_e32 v4, v8, v4
	v_max_u32_e32 v8, v10, v11
	v_min_u32_e32 v10, v10, v11
	v_max_u32_e32 v59, v60, v63
	v_min_u32_e32 v60, v60, v63
	v_max_u32_e32 v63, v62, v61
	v_min_u32_e32 v61, v62, v61
	v_max_u32_e32 v62, v64, v51
	v_min_u32_e32 v51, v64, v51
	v_max_u32_e32 v64, v49, v48
	v_min_u32_e32 v48, v49, v48
	v_max_u32_e32 v49, v53, v54
	v_min_u32_e32 v53, v53, v54
	v_max_u32_e32 v54, v57, v50
	v_min_u32_e32 v50, v57, v50
	v_max_u32_e32 v57, v58, v52
	v_min_u32_e32 v52, v58, v52
	v_max_u32_e32 v58, v56, v55
	v_min_u32_e32 v55, v56, v55
	v_max_u32_e32 v43, v44, v47
	v_min_u32_e32 v44, v44, v47
	v_max_u32_e32 v47, v46, v45
	v_min_u32_e32 v45, v46, v45
	v_max_u32_e32 v46, v72, v35
	v_min_u32_e32 v35, v72, v35
	v_max_u32_e32 v72, v33, v32
	v_min_u32_e32 v32, v33, v32
	v_max_u32_e32 v33, v37, v38
	v_min_u32_e32 v37, v37, v38
	v_max_u32_e32 v38, v41, v34
	v_min_u32_e32 v34, v41, v34
	v_max_u32_e32 v41, v42, v36
	v_min_u32_e32 v36, v42, v36
	v_max_u32_e32 v42, v40, v39
	v_min_u32_e32 v39, v40, v39
	v_max_u32_e32 v27, v28, v31
	v_min_u32_e32 v28, v28, v31
	v_max_u32_e32 v31, v30, v29
	v_min_u32_e32 v29, v30, v29
	v_max_u32_e32 v30, v80, v19
	v_min_u32_e32 v19, v80, v19
	v_max_u32_e32 v80, v17, v16
	v_min_u32_e32 v16, v17, v16
	v_max_u32_e32 v17, v21, v22
	v_min_u32_e32 v21, v21, v22
	v_max_u32_e32 v22, v25, v18
	v_min_u32_e32 v18, v25, v18
	v_max_u32_e32 v25, v26, v20
	v_min_u32_e32 v20, v26, v20
	v_max_u32_e32 v26, v24, v23
	v_min_u32_e32 v23, v24, v23
	v_max_u32_e32 v11, v12, v15
	v_min_u32_e32 v12, v12, v15
	v_max_u32_e32 v15, v14, v13
	v_min_u32_e32 v13, v14, v13
	v_max_u32_e32 v14, v88, v3
	v_min_u32_e32 v3, v88, v3
	v_max_u32_e32 v88, v1, v0
	v_min_u32_e32 v0, v1, v0
	v_max_u32_e32 v1, v5, v6
	v_min_u32_e32 v5, v5, v6
	v_max_u32_e32 v6, v9, v2
	v_min_u32_e32 v2, v9, v2
	v_max_u32_e32 v9, v10, v4
	v_min_u32_e32 v4, v10, v4
	v_max_u32_e32 v10, v8, v7
	v_min_u32_e32 v7, v8, v7
	v_max_u32_e32 v56, v59, v53
	v_min_u32_e32 v53, v59, v53
	v_max_u32_e32 v59, v60, v49
	v_min_u32_e32 v49, v60, v49
	v_max_u32_e32 v60, v63, v50
	v_min_u32_e32 v50, v63, v50
	v_max_u32_e32 v63, v61, v54
	v_min_u32_e32 v54, v61, v54
	v_max_u32_e32 v61, v62, v52
	v_min_u32_e32 v52, v62, v52
	v_max_u32_e32 v62, v51, v57
	v_min_u32_e32 v51, v51, v57
	v_max_u32_e32 v57, v64, v55
	v_min_u32_e32 v55, v64, v55
	v_max_u32_e32 v64, v48, v58
	v_min_u32_e32 v48, v48, v58
	v_max_u32_e32 v40, v43, v37
	v_min_u32_e32 v37, v43, v37
	v_max_u32_e32 v43, v44, v33
	v_min_u32_e32 v33, v44, v33
	v_max_u32_e32 v44, v47, v34
	v_min_u32_e32 v34, v47, v34
	v_max_u32_e32 v47, v45, v38
	v_min_u32_e32 v38, v45, v38
	v_max_u32_e32 v45, v46, v36
	v_min_u32_e32 v36, v46, v36
	v_max_u32_e32 v46, v35, v41
	v_min_u32_e32 v35, v35, v41
	v_max_u32_e32 v41, v72, v39
	v_min_u32_e32 v39, v72, v39
	v_max_u32_e32 v72, v32, v42
	v_min_u32_e32 v32, v32, v42
	v_max_u32_e32 v24, v27, v21
	v_min_u32_e32 v21, v27, v21
	v_max_u32_e32 v27, v28, v17
	v_min_u32_e32 v17, v28, v17
	v_max_u32_e32 v28, v31, v18
	v_min_u32_e32 v18, v31, v18
	v_max_u32_e32 v31, v29, v22
	v_min_u32_e32 v22, v29, v22
	v_max_u32_e32 v29, v30, v20
	v_min_u32_e32 v20, v30, v20
	v_max_u32_e32 v30, v19, v25
	v_min_u32_e32 v19, v19, v25
; DEV void sort16_desc(unsigned (&x)[16]) {
; #pragma unroll
;   for (int k = 2; k <= 16; k <<= 1)
; #pragma unroll
;     for (int j = k >> 1; j > 0; j >>= 1)
; #pragma unroll
;       for (int i = 0; i < 16; ++i) {
;         const int p = i ^ j;
;         if (p > i) {
;           if ((i & k) == 0) { TK_CE(x[i], x[p]); } else { TK_CE(x[p], x[i]); }
;         }
;       }
; }
; DEV void merge_top16(unsigned (&x)[16], const unsigned (&y)[16]) {
; #pragma unroll
;   for (int i = 0; i < 16; ++i) x[i] = max(x[i], y[15 - i]);
; #pragma unroll
;   for (int j = 8; j > 0; j >>= 1)
; #pragma unroll
;     for (int i = 0; i < 16; ++i) {
;       const int p = i ^ j;
;       if (p > i) { TK_CE(x[i], x[p]); }
;     }
; }
; __device__ void peer_q_topk_item(const Params& P, int l, int item, char* smem) {
;     ...
;       sort16_desc(Lc); sort16_desc(G1); sort16_desc(G2); sort16_desc(G3);
;       merge_top16(Lc, G1); merge_top16(G2, G3); merge_top16(Lc, G2);
	v_max_u32_e32 v25, v80, v23
	v_min_u32_e32 v23, v80, v23
	v_max_u32_e32 v80, v16, v26
	v_min_u32_e32 v16, v16, v26
	v_max_u32_e32 v8, v11, v5
	v_min_u32_e32 v5, v11, v5
	v_max_u32_e32 v11, v12, v1
	v_min_u32_e32 v1, v12, v1
	v_max_u32_e32 v12, v15, v2
	v_min_u32_e32 v2, v15, v2
	v_max_u32_e32 v15, v13, v6
	v_min_u32_e32 v6, v13, v6
	v_max_u32_e32 v13, v14, v4
	v_min_u32_e32 v4, v14, v4
	v_max_u32_e32 v14, v3, v9
	v_min_u32_e32 v3, v3, v9
	v_max_u32_e32 v9, v88, v7
	v_min_u32_e32 v7, v88, v7
	v_max_u32_e32 v88, v0, v10
	v_min_u32_e32 v0, v0, v10
	v_max_u32_e32 v58, v56, v61
	v_min_u32_e32 v56, v56, v61
	v_max_u32_e32 v61, v59, v62
	v_min_u32_e32 v59, v59, v62
	v_max_u32_e32 v62, v60, v57
	v_min_u32_e32 v57, v60, v57
	v_max_u32_e32 v60, v63, v64
	v_min_u32_e32 v63, v63, v64
	v_max_u32_e32 v64, v53, v52
	v_min_u32_e32 v52, v53, v52
	v_max_u32_e32 v53, v49, v51
	v_min_u32_e32 v49, v49, v51
	v_max_u32_e32 v51, v50, v55
	v_min_u32_e32 v50, v50, v55
	v_max_u32_e32 v55, v54, v48
	v_min_u32_e32 v48, v54, v48
	v_max_u32_e32 v42, v40, v45
	v_min_u32_e32 v40, v40, v45
	v_max_u32_e32 v45, v43, v46
	v_min_u32_e32 v43, v43, v46
	v_max_u32_e32 v46, v44, v41
	v_min_u32_e32 v41, v44, v41
	v_max_u32_e32 v44, v47, v72
	v_min_u32_e32 v47, v47, v72
	v_max_u32_e32 v72, v37, v36
	v_min_u32_e32 v36, v37, v36
	v_max_u32_e32 v37, v33, v35
	v_min_u32_e32 v33, v33, v35
	v_max_u32_e32 v35, v34, v39
	v_min_u32_e32 v34, v34, v39
	v_max_u32_e32 v39, v38, v32
	v_min_u32_e32 v32, v38, v32
	v_max_u32_e32 v26, v24, v29
	v_min_u32_e32 v24, v24, v29
	v_max_u32_e32 v29, v27, v30
	v_min_u32_e32 v27, v27, v30
	v_max_u32_e32 v30, v28, v25
	v_min_u32_e32 v25, v28, v25
	v_max_u32_e32 v28, v31, v80
	v_min_u32_e32 v31, v31, v80
	v_max_u32_e32 v80, v21, v20
	v_min_u32_e32 v20, v21, v20
	v_max_u32_e32 v21, v17, v19
	v_min_u32_e32 v17, v17, v19
	v_max_u32_e32 v19, v18, v23
	v_min_u32_e32 v18, v18, v23
	v_max_u32_e32 v23, v22, v16
	v_min_u32_e32 v16, v22, v16
	v_max_u32_e32 v10, v8, v13
	v_min_u32_e32 v8, v8, v13
	v_max_u32_e32 v13, v11, v14
	v_min_u32_e32 v11, v11, v14
	v_max_u32_e32 v14, v12, v9
	v_min_u32_e32 v9, v12, v9
	v_max_u32_e32 v12, v15, v88
	v_min_u32_e32 v15, v15, v88
	v_max_u32_e32 v88, v5, v4
	v_min_u32_e32 v4, v5, v4
	v_max_u32_e32 v5, v1, v3
	v_min_u32_e32 v1, v1, v3
	v_max_u32_e32 v3, v2, v7
	v_min_u32_e32 v2, v2, v7
	v_max_u32_e32 v7, v6, v0
	v_min_u32_e32 v0, v6, v0
	v_max_u32_e32 v54, v58, v62
	v_min_u32_e32 v58, v58, v62
	v_max_u32_e32 v62, v61, v60
	v_min_u32_e32 v60, v61, v60
	v_max_u32_e32 v61, v56, v57
	v_min_u32_e32 v56, v56, v57
	v_max_u32_e32 v57, v59, v63
	v_min_u32_e32 v59, v59, v63
	v_max_u32_e32 v63, v64, v51
	v_min_u32_e32 v51, v64, v51
	v_max_u32_e32 v64, v53, v55
	v_min_u32_e32 v53, v53, v55
	v_max_u32_e32 v55, v52, v50
	v_min_u32_e32 v50, v52, v50
	v_max_u32_e32 v52, v49, v48
	v_min_u32_e32 v48, v49, v48
	v_max_u32_e32 v38, v42, v46
	v_min_u32_e32 v42, v42, v46
	v_max_u32_e32 v46, v45, v44
	v_min_u32_e32 v44, v45, v44
	v_max_u32_e32 v45, v40, v41
	v_min_u32_e32 v40, v40, v41
	v_max_u32_e32 v41, v43, v47
	v_min_u32_e32 v43, v43, v47
	v_max_u32_e32 v47, v72, v35
	v_min_u32_e32 v35, v72, v35
	v_max_u32_e32 v72, v37, v39
	v_min_u32_e32 v37, v37, v39
	v_max_u32_e32 v39, v36, v34
	v_min_u32_e32 v34, v36, v34
	v_max_u32_e32 v36, v33, v32
	v_min_u32_e32 v32, v33, v32
	v_max_u32_e32 v22, v26, v30
	v_min_u32_e32 v26, v26, v30
	v_max_u32_e32 v30, v29, v28
	v_min_u32_e32 v28, v29, v28
	v_max_u32_e32 v29, v24, v25
	v_min_u32_e32 v24, v24, v25
	v_max_u32_e32 v25, v27, v31
	v_min_u32_e32 v27, v27, v31
	v_max_u32_e32 v31, v80, v19
	v_min_u32_e32 v19, v80, v19
	v_max_u32_e32 v80, v21, v23
	v_min_u32_e32 v21, v21, v23
	v_max_u32_e32 v23, v20, v18
	v_min_u32_e32 v18, v20, v18
	v_max_u32_e32 v20, v17, v16
	v_min_u32_e32 v16, v17, v16
	v_max_u32_e32 v6, v10, v14
	v_min_u32_e32 v10, v10, v14
	v_max_u32_e32 v14, v13, v12
	v_min_u32_e32 v12, v13, v12
	v_max_u32_e32 v13, v8, v9
	v_min_u32_e32 v8, v8, v9
	v_max_u32_e32 v9, v11, v15
	v_min_u32_e32 v11, v11, v15
	v_max_u32_e32 v15, v88, v3
	v_min_u32_e32 v3, v88, v3
	v_max_u32_e32 v88, v5, v7
	v_min_u32_e32 v5, v5, v7
	v_max_u32_e32 v7, v4, v2
	v_min_u32_e32 v2, v4, v2
	v_max_u32_e32 v4, v1, v0
	v_min_u32_e32 v0, v1, v0
	v_min_u32_e32 v49, v54, v62
	v_min_u32_e32 v65, v58, v60
	v_min_u32_e32 v66, v61, v57
	v_min_u32_e32 v67, v56, v59
	v_min_u32_e32 v68, v63, v64
	v_min_u32_e32 v69, v51, v53
	v_min_u32_e32 v70, v55, v52
	v_min_u32_e32 v71, v50, v48
	v_min_u32_e32 v33, v38, v46
	v_min_u32_e32 v73, v42, v44
	v_min_u32_e32 v74, v45, v41
	v_min_u32_e32 v75, v40, v43
	v_min_u32_e32 v76, v47, v72
	v_min_u32_e32 v77, v35, v37
	v_min_u32_e32 v78, v39, v36
	v_min_u32_e32 v79, v34, v32
	v_min_u32_e32 v17, v22, v30
	v_min_u32_e32 v81, v26, v28
	v_min_u32_e32 v82, v29, v25
	v_min_u32_e32 v83, v24, v27
	v_min_u32_e32 v84, v31, v80
	v_min_u32_e32 v85, v19, v21
	v_min_u32_e32 v86, v23, v20
	v_min_u32_e32 v87, v18, v16
	v_min_u32_e32 v1, v6, v14
	v_min_u32_e32 v89, v10, v12
	v_min_u32_e32 v90, v13, v9
	v_min_u32_e32 v91, v8, v11
	v_min_u32_e32 v92, v15, v88
	v_min_u32_e32 v93, v3, v5
	v_min_u32_e32 v94, v7, v4
	v_min_u32_e32 v95, v2, v0
	v_max3_u32 v54, v54, v62, v79
	v_max3_u32 v32, v49, v34, v32
	v_max3_u32 v34, v58, v60, v78
	v_max3_u32 v36, v65, v39, v36
	v_max3_u32 v39, v61, v57, v77
	v_max3_u32 v35, v66, v35, v37
	v_max3_u32 v37, v56, v59, v76
	v_max3_u32 v47, v67, v47, v72
	v_max3_u32 v49, v63, v64, v75
	v_max3_u32 v40, v68, v40, v43
	v_max3_u32 v43, v51, v53, v74
	v_max3_u32 v41, v69, v45, v41
	v_max3_u32 v45, v55, v52, v73
	v_max3_u32 v42, v70, v42, v44
	v_max3_u32 v33, v50, v48, v33
	v_max3_u32 v38, v71, v38, v46
	v_max3_u32 v22, v22, v30, v95
; DEV unsigned xor32_u(unsigned v) { return (unsigned)__shfl_xor((int)v, 32, 64); }
; DEV void merge_top16(unsigned (&x)[16], const unsigned (&y)[16]) {
; #pragma unroll
;   for (int i = 0; i < 16; ++i) x[i] = max(x[i], y[15 - i]);
; #pragma unroll
;   for (int j = 8; j > 0; j >>= 1)
; #pragma unroll
;     for (int i = 0; i < 16; ++i) {
;       const int p = i ^ j;
;       if (p > i) { TK_CE(x[i], x[p]); }
;     }
; }
; __device__ void peer_q_topk_item(const Params& P, int l, int item, char* smem) {
;     ...
;       sort16_desc(Lc); sort16_desc(G1); sort16_desc(G2); sort16_desc(G3);
;       merge_top16(Lc, G1); merge_top16(G2, G3); merge_top16(Lc, G2);
;     }
;     {
;       unsigned oth[16];
; #pragma unroll
;       for (int i = 0; i < 16; ++i) oth[i] = xor32_u(Lc[i]);
;       merge_top16(Lc, oth);
	v_max3_u32 v0, v17, v2, v0
	v_max3_u32 v2, v26, v28, v94
	v_max3_u32 v4, v81, v7, v4
	v_max3_u32 v7, v29, v25, v93
	v_max3_u32 v3, v82, v3, v5
	v_max3_u32 v5, v24, v27, v92
	v_max3_u32 v15, v83, v15, v88
	v_max3_u32 v17, v31, v80, v91
	v_max3_u32 v8, v84, v8, v11
	v_max3_u32 v11, v19, v21, v90
	v_max3_u32 v9, v85, v13, v9
	v_max3_u32 v13, v23, v20, v89
	v_max3_u32 v10, v86, v10, v12
	v_max3_u32 v1, v18, v16, v1
	v_max3_u32 v6, v87, v6, v14
	v_max_u32_e32 v44, v54, v49
	v_min_u32_e32 v46, v54, v49
	v_max_u32_e32 v48, v32, v40
	v_min_u32_e32 v32, v32, v40
	v_max_u32_e32 v40, v34, v43
	v_min_u32_e32 v34, v34, v43
	v_max_u32_e32 v43, v36, v41
	v_min_u32_e32 v36, v36, v41
	v_max_u32_e32 v41, v39, v45
	v_min_u32_e32 v39, v39, v45
	v_max_u32_e32 v45, v35, v42
	v_min_u32_e32 v35, v35, v42
	v_max_u32_e32 v42, v37, v33
	v_min_u32_e32 v33, v37, v33
	v_max_u32_e32 v37, v47, v38
	v_min_u32_e32 v38, v47, v38
	v_max_u32_e32 v12, v22, v17
	v_min_u32_e32 v14, v22, v17
	v_max_u32_e32 v16, v0, v8
	v_min_u32_e32 v0, v0, v8
	v_max_u32_e32 v8, v2, v11
	v_min_u32_e32 v2, v2, v11
	v_max_u32_e32 v11, v4, v9
	v_min_u32_e32 v4, v4, v9
	v_max_u32_e32 v9, v7, v13
	v_min_u32_e32 v7, v7, v13
	v_max_u32_e32 v13, v3, v10
	v_min_u32_e32 v3, v3, v10
	v_max_u32_e32 v10, v5, v1
	v_min_u32_e32 v1, v5, v1
	v_max_u32_e32 v5, v15, v6
	v_min_u32_e32 v6, v15, v6
	v_max_u32_e32 v47, v44, v41
	v_min_u32_e32 v41, v44, v41
	v_max_u32_e32 v44, v48, v45
	v_min_u32_e32 v45, v48, v45
	v_max_u32_e32 v48, v40, v42
	v_min_u32_e32 v40, v40, v42
	v_max_u32_e32 v42, v43, v37
	v_min_u32_e32 v37, v43, v37
	v_max_u32_e32 v43, v46, v39
	v_min_u32_e32 v39, v46, v39
	v_max_u32_e32 v46, v32, v35
	v_min_u32_e32 v32, v32, v35
	v_max_u32_e32 v35, v34, v33
	v_min_u32_e32 v33, v34, v33
	v_max_u32_e32 v34, v36, v38
	v_min_u32_e32 v36, v36, v38
	v_max_u32_e32 v15, v12, v9
	v_min_u32_e32 v9, v12, v9
	v_max_u32_e32 v12, v16, v13
	v_min_u32_e32 v13, v16, v13
	v_max_u32_e32 v16, v8, v10
	v_min_u32_e32 v8, v8, v10
	v_max_u32_e32 v10, v11, v5
	v_min_u32_e32 v5, v11, v5
	v_max_u32_e32 v11, v14, v7
	v_min_u32_e32 v7, v14, v7
	v_max_u32_e32 v14, v0, v3
	v_min_u32_e32 v0, v0, v3
	v_max_u32_e32 v3, v2, v1
	v_min_u32_e32 v1, v2, v1
	v_max_u32_e32 v2, v4, v6
	v_min_u32_e32 v4, v4, v6
	v_max_u32_e32 v38, v47, v48
	v_min_u32_e32 v47, v47, v48
	v_max_u32_e32 v48, v44, v42
	v_min_u32_e32 v42, v44, v42
	v_max_u32_e32 v44, v41, v40
	v_min_u32_e32 v40, v41, v40
	v_max_u32_e32 v41, v45, v37
	v_min_u32_e32 v37, v45, v37
	v_max_u32_e32 v45, v43, v35
	v_min_u32_e32 v35, v43, v35
	v_max_u32_e32 v43, v46, v34
	v_min_u32_e32 v34, v46, v34
	v_max_u32_e32 v46, v39, v33
	v_min_u32_e32 v33, v39, v33
	v_max_u32_e32 v39, v32, v36
	v_min_u32_e32 v32, v32, v36
	v_max_u32_e32 v6, v15, v16
	v_min_u32_e32 v15, v15, v16
	v_max_u32_e32 v16, v12, v10
	v_min_u32_e32 v10, v12, v10
	v_max_u32_e32 v12, v9, v8
	v_min_u32_e32 v8, v9, v8
	v_max_u32_e32 v9, v13, v5
	v_min_u32_e32 v5, v13, v5
	v_max_u32_e32 v13, v11, v3
	v_min_u32_e32 v3, v11, v3
	v_max_u32_e32 v11, v14, v2
	v_min_u32_e32 v2, v14, v2
	v_max_u32_e32 v14, v7, v1
	v_min_u32_e32 v1, v7, v1
	v_max_u32_e32 v7, v0, v4
	v_min_u32_e32 v0, v0, v4
	v_min_u32_e32 v36, v38, v48
	v_min_u32_e32 v49, v47, v42
	v_min_u32_e32 v50, v44, v41
	v_min_u32_e32 v51, v40, v37
	v_min_u32_e32 v52, v45, v43
	v_min_u32_e32 v53, v35, v34
	v_min_u32_e32 v54, v46, v39
	v_min_u32_e32 v55, v33, v32
	v_min_u32_e32 v4, v6, v16
	v_min_u32_e32 v17, v15, v10
	v_min_u32_e32 v18, v12, v9
	v_min_u32_e32 v19, v8, v5
	v_min_u32_e32 v20, v13, v11
	v_min_u32_e32 v21, v3, v2
	v_min_u32_e32 v22, v14, v7
	v_min_u32_e32 v23, v1, v0
	v_max3_u32 v23, v38, v48, v23
	v_max3_u32 v0, v36, v1, v0
	v_max3_u32 v1, v47, v42, v22
	v_max3_u32 v7, v49, v14, v7
	v_max3_u32 v14, v44, v41, v21
	v_max3_u32 v2, v50, v3, v2
	v_max3_u32 v3, v40, v37, v20
	v_max3_u32 v11, v51, v13, v11
	v_max3_u32 v13, v45, v43, v19
	v_max3_u32 v5, v52, v8, v5
	v_max3_u32 v8, v35, v34, v18
	v_max3_u32 v9, v53, v12, v9
	v_max3_u32 v12, v46, v39, v17
	v_max3_u32 v10, v54, v15, v10
	v_max3_u32 v4, v33, v32, v4
	v_max3_u32 v6, v55, v6, v16
	v_max_u32_e32 v15, v23, v13
	v_min_u32_e32 v13, v23, v13
	v_max_u32_e32 v16, v0, v5
	v_min_u32_e32 v0, v0, v5
	v_max_u32_e32 v5, v1, v8
	v_min_u32_e32 v1, v1, v8
	v_max_u32_e32 v8, v7, v9
	v_min_u32_e32 v7, v7, v9
	v_max_u32_e32 v9, v14, v12
	v_min_u32_e32 v12, v14, v12
	v_max_u32_e32 v14, v2, v10
	v_min_u32_e32 v2, v2, v10
	v_max_u32_e32 v10, v3, v4
	v_min_u32_e32 v3, v3, v4
	v_max_u32_e32 v4, v11, v6
	v_min_u32_e32 v6, v11, v6
	v_max_u32_e32 v11, v15, v9
	v_min_u32_e32 v9, v15, v9
	v_max_u32_e32 v15, v16, v14
	v_min_u32_e32 v14, v16, v14
	v_max_u32_e32 v16, v5, v10
	v_min_u32_e32 v5, v5, v10
	v_max_u32_e32 v10, v8, v4
	v_min_u32_e32 v4, v8, v4
	v_max_u32_e32 v8, v13, v12
	v_min_u32_e32 v12, v13, v12
	v_max_u32_e32 v13, v0, v2
	v_min_u32_e32 v0, v0, v2
	v_max_u32_e32 v2, v1, v3
	v_min_u32_e32 v1, v1, v3
	v_max_u32_e32 v3, v7, v6
	v_min_u32_e32 v6, v7, v6
	v_max_u32_e32 v7, v11, v16
	v_min_u32_e32 v11, v11, v16
	v_max_u32_e32 v16, v15, v10
	v_min_u32_e32 v10, v15, v10
	v_max_u32_e32 v15, v9, v5
	v_min_u32_e32 v5, v9, v5
	v_max_u32_e32 v9, v14, v4
	v_min_u32_e32 v4, v14, v4
	v_max_u32_e32 v14, v8, v2
	v_min_u32_e32 v2, v8, v2
	v_max_u32_e32 v8, v13, v3
	v_min_u32_e32 v3, v13, v3
	v_max_u32_e32 v13, v12, v1
	v_min_u32_e32 v1, v12, v1
	v_max_u32_e32 v12, v0, v6
	v_min_u32_e32 v0, v0, v6
	v_max_u32_e32 v6, v7, v16
	v_min_u32_e32 v7, v7, v16
	v_max_u32_e32 v16, v11, v10
	v_min_u32_e32 v10, v11, v10
	v_max_u32_e32 v11, v15, v9
	v_min_u32_e32 v9, v15, v9
	v_max_u32_e32 v15, v5, v4
	v_min_u32_e32 v4, v5, v4
	v_max_u32_e32 v5, v14, v8
	v_min_u32_e32 v8, v14, v8
	v_max_u32_e32 v14, v2, v3
	v_min_u32_e32 v2, v2, v3
	v_max_u32_e32 v3, v13, v12
	v_min_u32_e32 v12, v13, v12
	v_max_u32_e32 v13, v1, v0
	v_min_u32_e32 v0, v1, v0
	ds_bpermute_b32 v1, v162, v6
	ds_bpermute_b32 v17, v162, v7
	ds_bpermute_b32 v18, v162, v16
	ds_bpermute_b32 v19, v162, v10
	ds_bpermute_b32 v20, v162, v11
	ds_bpermute_b32 v21, v162, v9
	ds_bpermute_b32 v22, v162, v15
	ds_bpermute_b32 v23, v162, v4
	ds_bpermute_b32 v24, v162, v5
	ds_bpermute_b32 v25, v162, v8
	ds_bpermute_b32 v26, v162, v14
	ds_bpermute_b32 v27, v162, v2
	ds_bpermute_b32 v28, v162, v3
	ds_bpermute_b32 v29, v162, v12
	ds_bpermute_b32 v30, v162, v13
	ds_bpermute_b32 v31, v162, v0
	s_waitcnt lgkmcnt(4)
; DEV unsigned xor32_u(unsigned v) { return (unsigned)__shfl_xor((int)v, 32, 64); }
; __device__ void peer_q_topk_item(const Params& P, int l, int item, char* smem) {
;     ...
;     {
;       unsigned oth[16];
; #pragma unroll
;       for (int i = 0; i < 16; ++i) oth[i] = xor32_u(Lc[i]);
;       merge_top16(Lc, oth);
;     }
; #pragma unroll
;     for (int i = 0; i < 16; ++i) { L0[i] = L1[i]; L1[i] = Lc[i]; }
;   }
	v_max_u32_e32 v11, v11, v27
	s_waitcnt lgkmcnt(3)
	v_max_u32_e32 v10, v10, v28
	s_waitcnt lgkmcnt(2)
	v_max_u32_e32 v16, v16, v29
	s_waitcnt lgkmcnt(1)
	v_max_u32_e32 v7, v7, v30
	s_waitcnt lgkmcnt(0)
	v_max_u32_e32 v6, v6, v31
	v_max_u32_e32 v9, v9, v26
	v_max_u32_e32 v15, v15, v25
	v_max_u32_e32 v4, v4, v24
	v_max_u32_e32 v5, v5, v23
	v_max_u32_e32 v8, v8, v22
	v_max_u32_e32 v14, v14, v21
	v_max_u32_e32 v2, v2, v20
	v_max_u32_e32 v3, v3, v19
	v_max_u32_e32 v12, v12, v18
	v_max_u32_e32 v13, v13, v17
	v_max_u32_e32 v0, v0, v1
	v_max_u32_e32 v1, v6, v5
	v_min_u32_e32 v5, v6, v5
	v_max_u32_e32 v6, v7, v8
	v_min_u32_e32 v7, v7, v8
	v_max_u32_e32 v8, v16, v14
	v_min_u32_e32 v14, v16, v14
	v_max_u32_e32 v16, v10, v2
	v_min_u32_e32 v2, v10, v2
	v_max_u32_e32 v10, v11, v3
	v_min_u32_e32 v3, v11, v3
	v_max_u32_e32 v11, v9, v12
	v_min_u32_e32 v9, v9, v12
	v_max_u32_e32 v12, v15, v13
	v_min_u32_e32 v13, v15, v13
	v_max_u32_e32 v15, v4, v0
	v_min_u32_e32 v0, v4, v0
	v_max_u32_e32 v4, v1, v10
	v_min_u32_e32 v1, v1, v10
	v_max_u32_e32 v10, v6, v11
	v_min_u32_e32 v6, v6, v11
	v_max_u32_e32 v11, v8, v12
	v_min_u32_e32 v8, v8, v12
	v_max_u32_e32 v12, v16, v15
	v_min_u32_e32 v15, v16, v15
	v_max_u32_e32 v16, v5, v3
	v_min_u32_e32 v3, v5, v3
	v_max_u32_e32 v5, v7, v9
	v_min_u32_e32 v7, v7, v9
	v_max_u32_e32 v9, v14, v13
	v_min_u32_e32 v13, v14, v13
	v_max_u32_e32 v14, v2, v0
	v_min_u32_e32 v0, v2, v0
	v_max_u32_e32 v2, v4, v11
	v_min_u32_e32 v4, v4, v11
	v_max_u32_e32 v11, v10, v12
	v_min_u32_e32 v10, v10, v12
	v_max_u32_e32 v12, v1, v8
	v_min_u32_e32 v8, v1, v8
	v_max_u32_e32 v17, v6, v15
	v_min_u32_e32 v6, v6, v15
	v_max_u32_e32 v15, v16, v9
	v_min_u32_e32 v9, v16, v9
	v_max_u32_e32 v18, v5, v14
	v_min_u32_e32 v5, v5, v14
	v_max_u32_e32 v19, v3, v13
	v_min_u32_e32 v20, v3, v13
	v_max_u32_e32 v21, v7, v0
	v_min_u32_e32 v22, v7, v0
	v_max_u32_e32 v16, v2, v11
	v_min_u32_e32 v3, v2, v11
	v_max_u32_e32 v0, v4, v10
	v_min_u32_e32 v10, v4, v10
	v_max_u32_e32 v1, v12, v17
	v_min_u32_e32 v11, v12, v17
	v_max_u32_e32 v12, v8, v6
	v_min_u32_e32 v13, v8, v6
	v_max_u32_e32 v14, v15, v18
	v_min_u32_e32 v2, v15, v18
	v_max_u32_e32 v7, v9, v5
	v_min_u32_e32 v4, v9, v5
	v_max_u32_e32 v8, v19, v21
	v_min_u32_e32 v5, v19, v21
	v_max_u32_e32 v15, v20, v22
	v_min_u32_e32 v6, v20, v22
	s_mov_b64 s[38:39], 0
	s_and_b64 vcc, exec, s[0:1]
	s_cbranch_vccnz .LBB0_49
	v_mov_b32_e32 v119, v15
	v_mov_b32_e32 v115, v6
	v_mov_b32_e32 v101, v14
	v_mov_b32_e32 v103, v2
	v_mov_b32_e32 v96, v4
	v_mov_b32_e32 v97, v7
	v_mov_b32_e32 v107, v8
	v_mov_b32_e32 v111, v5
	v_mov_b32_e32 v158, v16
	v_mov_b32_e32 v168, v3
	v_mov_b32_e32 v165, v0
	v_mov_b32_e32 v155, v10
	v_mov_b32_e32 v123, v1
	v_mov_b32_e32 v131, v11
	v_mov_b32_e32 v135, v12
	v_mov_b32_e32 v127, v13
	s_branch .LBB0_45
